# mode-0 attention epilogue: gate loads batched (32 in flight), counted vmcnt, saddr park stores
# speedup vs baseline: 1.0128x; 1.0128x over previous
; template <int MODE>
; __device__ __forceinline__ void partialSM(f32x16& p0, f32x16& p1, float& m_reg, float& mn, float& alpha, int relh, int relw_min, int relw_max, const float* lut) {
;     ...
;     const float mnC = -mn * C;
; #pragma unroll
;     for (int r = 0; r < 16; ++r) p0[r] = fmaf(p0[r], C, mnC);
; #pragma unroll
;     for (int r = 0; r < 16; ++r) p1[r] = fmaf(p1[r], C, mnC);
; #pragma unroll
;     for (int r = 0; r < 16; ++r) p0[r] = __builtin_amdgcn_exp2f(p0[r]);
; __device__ __forceinline__ void finishSM(f32x16& p0, f32x16& p1, float alpha, float& l_reg, bf16x8& pa0, bf16x8& pa1, bf16x8& pa2, bf16x8& pa3) {
; #pragma unroll
;   for (int r = 0; r < 16; ++r) p1[r] = __builtin_amdgcn_exp2f(p1[r]);
;   float ps = 0;
; #pragma unroll
;   for (int r = 0; r < 16; ++r) ps += p0[r];
; #pragma unroll
;   for (int r = 0; r < 16; ++r) ps += p1[r];
;   { auto rr = __builtin_amdgcn_permlane32_swap(__float_as_uint(ps), __float_as_uint(ps), false, false);
;     ps = __uint_as_float(rr[0]) + __uint_as_float(rr[1]); }
;   l_reg = l_reg * alpha + ps;
;     ...
;   PK4(p0, 0, pa0); PK4(p0, 8, pa1); PK4(p1, 0, pa2); PK4(p1, 8, pa3);
.LBB0_95:
	v_cndmask_b32_e64 v101, v101, v166, s[0:1]
	v_mul_f32_e32 v101, 0xbe0293ee, v101
	v_fmamk_f32 v82, v82, 0x3e0293ee, v101
	v_fmamk_f32 v83, v83, 0x3e0293ee, v101
	v_fmamk_f32 v84, v84, 0x3e0293ee, v101
	v_fmamk_f32 v85, v85, 0x3e0293ee, v101
	v_fmamk_f32 v86, v86, 0x3e0293ee, v101
	v_fmamk_f32 v87, v87, 0x3e0293ee, v101
	v_fmamk_f32 v88, v88, 0x3e0293ee, v101
	v_fmamk_f32 v89, v89, 0x3e0293ee, v101
	v_fmamk_f32 v90, v90, 0x3e0293ee, v101
	v_fmamk_f32 v91, v91, 0x3e0293ee, v101
	v_fmamk_f32 v92, v92, 0x3e0293ee, v101
	v_fmamk_f32 v93, v93, 0x3e0293ee, v101
	v_fmamk_f32 v94, v94, 0x3e0293ee, v101
	v_fmamk_f32 v95, v95, 0x3e0293ee, v101
	v_fmamk_f32 v96, v96, 0x3e0293ee, v101
	v_fmamk_f32 v97, v97, 0x3e0293ee, v101
	v_fmamk_f32 v66, v66, 0x3e0293ee, v101
	v_fmamk_f32 v67, v67, 0x3e0293ee, v101
	v_fmamk_f32 v68, v68, 0x3e0293ee, v101
	v_fmamk_f32 v69, v69, 0x3e0293ee, v101
	v_fmamk_f32 v70, v70, 0x3e0293ee, v101
	v_fmamk_f32 v71, v71, 0x3e0293ee, v101
	v_fmamk_f32 v72, v72, 0x3e0293ee, v101
	v_fmamk_f32 v73, v73, 0x3e0293ee, v101
	v_fmamk_f32 v74, v74, 0x3e0293ee, v101
	v_fmamk_f32 v75, v75, 0x3e0293ee, v101
	v_fmamk_f32 v76, v76, 0x3e0293ee, v101
	v_fmamk_f32 v77, v77, 0x3e0293ee, v101
	v_fmamk_f32 v78, v78, 0x3e0293ee, v101
	v_fmamk_f32 v79, v79, 0x3e0293ee, v101
	v_fmamk_f32 v80, v80, 0x3e0293ee, v101
	v_fmac_f32_e32 v101, 0x3e0293ee, v81
	v_exp_f32_e32 v81, v82
	v_exp_f32_e32 v82, v83
	v_exp_f32_e32 v83, v84
	v_exp_f32_e32 v84, v85
	v_exp_f32_e32 v85, v86
	v_exp_f32_e32 v86, v87
	v_exp_f32_e32 v87, v88
	v_exp_f32_e32 v88, v89
	v_exp_f32_e32 v89, v90
	v_exp_f32_e32 v90, v91
	v_exp_f32_e32 v91, v92
	v_exp_f32_e32 v92, v93
	v_exp_f32_e32 v93, v94
	v_exp_f32_e32 v94, v95
	v_exp_f32_e32 v95, v96
	v_exp_f32_e32 v96, v97
	v_exp_f32_e32 v97, v66
	v_add_f32_e32 v66, 0, v81
	v_add_f32_e32 v66, v82, v66
	v_add_f32_e32 v66, v83, v66
	v_add_f32_e32 v66, v84, v66
	v_add_f32_e32 v66, v85, v66
	v_add_f32_e32 v66, v86, v66
	v_add_f32_e32 v66, v87, v66
	v_add_f32_e32 v66, v88, v66
	v_add_f32_e32 v66, v89, v66
	v_add_f32_e32 v66, v90, v66
	v_add_f32_e32 v66, v91, v66
	v_add_f32_e32 v66, v92, v66
	v_add_f32_e32 v66, v93, v66
	v_exp_f32_e32 v102, v67
	v_add_f32_e32 v66, v94, v66
	v_exp_f32_e32 v103, v68
	v_add_f32_e32 v66, v95, v66
	v_exp_f32_e32 v104, v69
	v_add_f32_e32 v66, v96, v66
	v_exp_f32_e32 v105, v70
	v_add_f32_e32 v66, v97, v66
	v_exp_f32_e32 v106, v71
	v_add_f32_e32 v66, v102, v66
	v_exp_f32_e32 v107, v72
	v_add_f32_e32 v66, v103, v66
	v_exp_f32_e32 v108, v73
	v_add_f32_e32 v66, v104, v66
	v_exp_f32_e32 v109, v74
	v_add_f32_e32 v66, v105, v66
	v_exp_f32_e32 v110, v75
	v_add_f32_e32 v66, v106, v66
	v_exp_f32_e32 v111, v76
	v_add_f32_e32 v66, v107, v66
	v_exp_f32_e32 v112, v77
	v_add_f32_e32 v66, v108, v66
	v_exp_f32_e32 v113, v78
	v_add_f32_e32 v66, v109, v66
	v_exp_f32_e32 v114, v79
	v_add_f32_e32 v66, v110, v66
	v_exp_f32_e32 v115, v80
	v_add_f32_e32 v66, v111, v66
	v_exp_f32_e32 v101, v101
	v_add_f32_e32 v66, v112, v66
	v_add_f32_e32 v66, v113, v66
	v_add_f32_e32 v66, v114, v66
	v_add_f32_e32 v66, v115, v66
	v_add_f32_e32 v66, v101, v66
	v_mov_b32_e32 v67, v66
	s_nop 1
	v_permlane32_swap_b32_e32 v66, v67
	v_cvt_pk_bf16_f32 v68, v81, v82
	v_cvt_pk_bf16_f32 v69, v83, v84
	v_cvt_pk_bf16_f32 v70, v85, v86
	v_cvt_pk_bf16_f32 v71, v87, v88
	v_cvt_pk_bf16_f32 v72, v89, v90
	v_cvt_pk_bf16_f32 v73, v91, v92
	v_cvt_pk_bf16_f32 v74, v93, v94
	v_cvt_pk_bf16_f32 v75, v95, v96
	v_cvt_pk_bf16_f32 v76, v97, v102
	v_cvt_pk_bf16_f32 v77, v103, v104
	v_cvt_pk_bf16_f32 v78, v105, v106
	v_cvt_pk_bf16_f32 v79, v107, v108
	v_cvt_pk_bf16_f32 v80, v109, v110
	v_cvt_pk_bf16_f32 v81, v111, v112
	v_cvt_pk_bf16_f32 v82, v113, v114
	v_cvt_pk_bf16_f32 v83, v115, v101
	v_permlane32_swap_b32_e32 v68, v70
	v_permlane32_swap_b32_e32 v69, v71
	v_permlane32_swap_b32_e32 v72, v74
	v_permlane32_swap_b32_e32 v73, v75
	v_permlane32_swap_b32_e32 v76, v78
	v_permlane32_swap_b32_e32 v77, v79
	v_permlane32_swap_b32_e32 v80, v82
	v_permlane32_swap_b32_e32 v81, v83
	ds_read_b64_tr_b16 v[84:85], v208 offset:0
	ds_read_b64_tr_b16 v[86:87], v208 offset:0x800
	ds_read_b64_tr_b16 v[88:89], v208 offset:0x1000
	ds_read_b64_tr_b16 v[90:91], v208 offset:0x1800
	ds_read_b64_tr_b16 v[92:93], v208 offset:0x2000
	ds_read_b64_tr_b16 v[94:95], v208 offset:0x2800
	ds_read_b64_tr_b16 v[102:103], v208 offset:0x3000
	ds_read_b64_tr_b16 v[104:105], v208 offset:0x3800
	s_waitcnt lgkmcnt(0)
	s_nop 0
	v_mfma_f32_32x32x16_bf16 v[18:33], v[68:71], v[84:87], v[18:33]
	ds_read_b64_tr_b16 v[84:85], v208 offset:0x200
	ds_read_b64_tr_b16 v[86:87], v208 offset:0xa00
	v_mfma_f32_32x32x16_bf16 v[18:33], v[72:75], v[88:91], v[18:33]
	ds_read_b64_tr_b16 v[88:89], v208 offset:0x1200
	ds_read_b64_tr_b16 v[90:91], v208 offset:0x1a00
	v_mfma_f32_32x32x16_bf16 v[18:33], v[76:79], v[92:95], v[18:33]
	ds_read_b64_tr_b16 v[92:93], v208 offset:0x2200
	ds_read_b64_tr_b16 v[94:95], v208 offset:0x2a00
	v_mfma_f32_32x32x16_bf16 v[18:33], v[80:83], v[102:105], v[18:33]
	ds_read_b64_tr_b16 v[102:103], v208 offset:0x3200
	ds_read_b64_tr_b16 v[104:105], v208 offset:0x3a00
	s_waitcnt lgkmcnt(0)
	v_mfma_f32_32x32x16_bf16 v[50:65], v[68:71], v[84:87], v[50:65]
	ds_read_b64_tr_b16 v[84:85], v208 offset:0x400
	ds_read_b64_tr_b16 v[86:87], v208 offset:0xc00
	v_mfma_f32_32x32x16_bf16 v[50:65], v[72:75], v[88:91], v[50:65]
	ds_read_b64_tr_b16 v[88:89], v208 offset:0x1400
	ds_read_b64_tr_b16 v[90:91], v208 offset:0x1c00
	v_mfma_f32_32x32x16_bf16 v[50:65], v[76:79], v[92:95], v[50:65]
	ds_read_b64_tr_b16 v[92:93], v208 offset:0x2400
	ds_read_b64_tr_b16 v[94:95], v208 offset:0x2c00
	v_mfma_f32_32x32x16_bf16 v[50:65], v[80:83], v[102:105], v[50:65]
	ds_read_b64_tr_b16 v[102:103], v208 offset:0x3400
	ds_read_b64_tr_b16 v[104:105], v208 offset:0x3c00
	s_waitcnt lgkmcnt(0)
; __device__ __forceinline__ float bf2f(bf16_t v) { return __uint_as_float(((unsigned)v) << 16); }
; __device__ __forceinline__ int crow(int r, int hi) { return (r & 3) + 8 * (r >> 2) + 4 * hi; }
; template <int MODE>
; __device__ __forceinline__ void attn_body(const bf16_t* __restrict__ Qb, const bf16_t* __restrict__ Kh, const bf16_t* __restrict__ Vh, int NT, int krel0,
;                                           char* lds, const float* __restrict__ lutg, const AttnEpi& E) {
;     ...
;   pv_d0(o, vb0 + oq, pa0, pa1, pa2, pa3);
;   if constexpr (MODE == 1) l_reg += __builtin_amdgcn_exp2f(E.sinkl2 - m_reg);
;   if (hi == 0) li_l[r32] = l_reg; asm volatile("s_waitcnt lgkmcnt(0)" ::: "memory");
;   float rli[16];
; #pragma unroll
;   for (int r = 0; r < 16; ++r) rli[r] = __builtin_amdgcn_rcpf(li_l[crow(r, hi)]);
;   float* pk0 = E.park; float* pk1 = E.park + 64 * 512;
;   const int rowb = wid * 32;
;   if constexpr (MODE == 0 || MODE == 1) {
; #pragma unroll
;     for (int r = 0; r < 16; ++r) { const int row = rowb + crow(r, hi);
; #pragma unroll
;       for (int d0 = 0; d0 < 4; ++d0) { const int idx = (d0 * 16 + r) * 512 + tid;
;         const float g = bf2f(E.gate[(size_t)row * GW + d0 * 32 + r32]);
;         const float v = o[d0][r] * rli[r] * g;
;         if constexpr (MODE == 0) pk0[idx] = v; else pk0[idx] += v; } }
	v_mfma_f32_32x32x16_bf16 v[34:49], v[68:71], v[84:87], v[34:49]
	ds_read_b64_tr_b16 v[84:85], v208 offset:0x600
	ds_read_b64_tr_b16 v[86:87], v208 offset:0xe00
	v_mfma_f32_32x32x16_bf16 v[34:49], v[72:75], v[88:91], v[34:49]
	ds_read_b64_tr_b16 v[88:89], v208 offset:0x1600
	ds_read_b64_tr_b16 v[90:91], v208 offset:0x1e00
	v_mfma_f32_32x32x16_bf16 v[34:49], v[76:79], v[92:95], v[34:49]
	ds_read_b64_tr_b16 v[92:93], v208 offset:0x2600
	ds_read_b64_tr_b16 v[94:95], v208 offset:0x2e00
	v_mfma_f32_32x32x16_bf16 v[34:49], v[80:83], v[102:105], v[34:49]
	ds_read_b64_tr_b16 v[102:103], v208 offset:0x3600
	ds_read_b64_tr_b16 v[104:105], v208 offset:0x3e00
	s_waitcnt lgkmcnt(0)
	v_mfma_f32_32x32x16_bf16 v[2:17], v[68:71], v[84:87], v[2:17]
	v_mfma_f32_32x32x16_bf16 v[2:17], v[72:75], v[88:91], v[2:17]
	v_mfma_f32_32x32x16_bf16 v[2:17], v[76:79], v[92:95], v[2:17]
	v_mfma_f32_32x32x16_bf16 v[2:17], v[80:83], v[102:105], v[2:17]
	s_and_saveexec_b64 s[0:1], s[6:7]
	v_add_f32_e32 v68, v98, v99
	v_fmac_f32_e32 v68, v207, v162
	v_add_f32_e32 v66, v66, v67
	v_fmac_f32_e32 v66, v68, v100
	ds_write_b32 v206, v66
	s_or_b64 exec, exec, s[0:1]
	s_waitcnt lgkmcnt(0)
	ds_read_b128 v[66:69], v0
	ds_read_b128 v[70:73], v0 offset:32
	s_mul_i32 s1, s54, 0x1800
	v_readlane_b32 s6, v252, 37
	s_mul_hi_i32 s0, s54, 0x1800
	s_waitcnt lgkmcnt(1)
	v_rcp_f32_e32 v81, v66
	v_rcp_f32_e32 v88, v67
	v_rcp_f32_e32 v89, v68
	v_rcp_f32_e32 v80, v69
	ds_read_b128 v[66:69], v0 offset:64
	ds_read_b128 v[82:85], v0 offset:96
	v_readlane_b32 s7, v252, 38
	s_add_u32 s1, s6, s1
	s_addc_u32 s0, s7, s0
	s_lshl_b32 s16, s63, 1
	s_add_u32 s56, s1, s16
	s_addc_u32 s57, s0, 0
	v_lshlrev_b32_e32 v0, 1, v189
	s_waitcnt lgkmcnt(1)
	v_rcp_f32_e32 v75, v66
	v_rcp_f32_e32 v74, v67
	v_lshl_add_u64 v[66:67], s[56:57], 0, v[0:1]
	v_or_b32_e32 v0, v205, v204
	v_rcp_f32_e32 v79, v70
	v_rcp_f32_e32 v78, v71
	s_waitcnt lgkmcnt(0)
	v_rcp_f32_e32 v71, v82
	v_rcp_f32_e32 v70, v83
	v_rcp_f32_e32 v77, v72
	v_rcp_f32_e32 v72, v69
	v_rcp_f32_e32 v69, v84
	v_ashrrev_i32_e32 v189, 31, v188
	v_rcp_f32_e32 v76, v73
	v_rcp_f32_e32 v73, v68
	v_rcp_f32_e32 v68, v85
	v_lshlrev_b32_e32 v134, 2, v188
	v_mad_i64_i32 v[130:131], s[28:29], v0, s88, v[66:67]
	global_load_ushort v98, v[130:131], off
	global_load_ushort v99, v[130:131], off offset:64
	global_load_ushort v100, v[130:131], off offset:128
	global_load_ushort v101, v[130:131], off offset:192
	v_or_b32_e32 v132, 1, v0
	v_mad_i64_i32 v[130:131], s[28:29], v132, s88, v[66:67]
	global_load_ushort v102, v[130:131], off
	global_load_ushort v103, v[130:131], off offset:64
	global_load_ushort v104, v[130:131], off offset:128
	global_load_ushort v105, v[130:131], off offset:192
	v_or_b32_e32 v132, 2, v0
	v_mad_i64_i32 v[130:131], s[28:29], v132, s88, v[66:67]
	global_load_ushort v106, v[130:131], off
	global_load_ushort v107, v[130:131], off offset:64
	global_load_ushort v108, v[130:131], off offset:128
	global_load_ushort v109, v[130:131], off offset:192
	v_or_b32_e32 v132, 3, v0
	v_mad_i64_i32 v[130:131], s[28:29], v132, s88, v[66:67]
	global_load_ushort v110, v[130:131], off
	global_load_ushort v111, v[130:131], off offset:64
	global_load_ushort v112, v[130:131], off offset:128
	global_load_ushort v113, v[130:131], off offset:192
	v_or_b32_e32 v132, 8, v0
	v_mad_i64_i32 v[130:131], s[28:29], v132, s88, v[66:67]
	global_load_ushort v114, v[130:131], off
	global_load_ushort v115, v[130:131], off offset:64
	global_load_ushort v116, v[130:131], off offset:128
	global_load_ushort v117, v[130:131], off offset:192
	v_or_b32_e32 v132, 9, v0
	v_mad_i64_i32 v[130:131], s[28:29], v132, s88, v[66:67]
	global_load_ushort v118, v[130:131], off
	global_load_ushort v119, v[130:131], off offset:64
	global_load_ushort v120, v[130:131], off offset:128
	global_load_ushort v121, v[130:131], off offset:192
	v_or_b32_e32 v132, 10, v0
	v_mad_i64_i32 v[130:131], s[28:29], v132, s88, v[66:67]
	global_load_ushort v122, v[130:131], off
	global_load_ushort v123, v[130:131], off offset:64
	global_load_ushort v124, v[130:131], off offset:128
	global_load_ushort v125, v[130:131], off offset:192
	v_or_b32_e32 v132, 11, v0
	v_mad_i64_i32 v[130:131], s[28:29], v132, s88, v[66:67]
	global_load_ushort v126, v[130:131], off
	global_load_ushort v127, v[130:131], off offset:64
	global_load_ushort v128, v[130:131], off offset:128
	global_load_ushort v129, v[130:131], off offset:192
	s_add_u32 s20, s34, 0x0
	s_addc_u32 s21, s35, 0
	s_add_u32 s22, s34, 0x8000
	s_addc_u32 s23, s35, 0
	s_add_u32 s24, s34, 0x10000
	s_addc_u32 s25, s35, 0
	s_add_u32 s26, s34, 0x18000
	s_addc_u32 s27, s35, 0
	s_waitcnt vmcnt(31)
	v_lshlrev_b32_e32 v98, 16, v98
	v_mul_f32_e32 v18, v18, v81
	v_mul_f32_e32 v98, v18, v98
	global_store_dword v134, v98, s[20:21]
	s_waitcnt vmcnt(31)
	v_lshlrev_b32_e32 v99, 16, v99
	v_mul_f32_e32 v50, v50, v81
	v_mul_f32_e32 v99, v50, v99
	global_store_dword v134, v99, s[22:23]
	s_waitcnt vmcnt(31)
	v_lshlrev_b32_e32 v100, 16, v100
	v_mul_f32_e32 v34, v34, v81
	v_mul_f32_e32 v100, v34, v100
	global_store_dword v134, v100, s[24:25]
	s_waitcnt vmcnt(31)
	v_lshlrev_b32_e32 v101, 16, v101
	v_mul_f32_e32 v2, v2, v81
	v_mul_f32_e32 v101, v2, v101
	global_store_dword v134, v101, s[26:27]
	s_waitcnt vmcnt(31)
	v_lshlrev_b32_e32 v102, 16, v102
	v_mul_f32_e32 v19, v19, v88
	v_mul_f32_e32 v102, v19, v102
	global_store_dword v134, v102, s[20:21] offset:2048
	s_waitcnt vmcnt(31)
	v_lshlrev_b32_e32 v103, 16, v103
	v_mul_f32_e32 v51, v51, v88
	v_mul_f32_e32 v103, v51, v103
	global_store_dword v134, v103, s[22:23] offset:2048
	s_waitcnt vmcnt(31)
; __device__ __forceinline__ float bf2f(bf16_t v) { return __uint_as_float(((unsigned)v) << 16); }
; __device__ __forceinline__ int crow(int r, int hi) { return (r & 3) + 8 * (r >> 2) + 4 * hi; }
; template <int MODE>
; __device__ __forceinline__ void attn_body(const bf16_t* __restrict__ Qb, const bf16_t* __restrict__ Kh, const bf16_t* __restrict__ Vh, int NT, int krel0,
;                                           char* lds, const float* __restrict__ lutg, const AttnEpi& E) {
;     ...
;     for (int r = 0; r < 16; ++r) { const int row = rowb + crow(r, hi);
; #pragma unroll
;       for (int d0 = 0; d0 < 4; ++d0) { const int idx = (d0 * 16 + r) * 512 + tid;
;         const float g = bf2f(E.gate[(size_t)row * GW + d0 * 32 + r32]);
;         const float v = o[d0][r] * rli[r] * g;
;         if constexpr (MODE == 0) pk0[idx] = v; else pk0[idx] += v; } }
	v_lshlrev_b32_e32 v104, 16, v104
	v_mul_f32_e32 v35, v35, v88
	v_mul_f32_e32 v104, v35, v104
	global_store_dword v134, v104, s[24:25] offset:2048
	s_waitcnt vmcnt(31)
	v_lshlrev_b32_e32 v105, 16, v105
	v_mul_f32_e32 v3, v3, v88
	v_mul_f32_e32 v105, v3, v105
	global_store_dword v134, v105, s[26:27] offset:2048
	s_add_u32 s20, s34, 0x1000
	s_addc_u32 s21, s35, 0
	s_add_u32 s22, s34, 0x9000
	s_addc_u32 s23, s35, 0
	s_add_u32 s24, s34, 0x11000
	s_addc_u32 s25, s35, 0
	s_add_u32 s26, s34, 0x19000
	s_addc_u32 s27, s35, 0
	s_waitcnt vmcnt(31)
	v_lshlrev_b32_e32 v106, 16, v106
	v_mul_f32_e32 v20, v20, v89
	v_mul_f32_e32 v106, v20, v106
	global_store_dword v134, v106, s[20:21]
	s_waitcnt vmcnt(31)
	v_lshlrev_b32_e32 v107, 16, v107
	v_mul_f32_e32 v52, v52, v89
	v_mul_f32_e32 v107, v52, v107
	global_store_dword v134, v107, s[22:23]
	s_waitcnt vmcnt(31)
	v_lshlrev_b32_e32 v108, 16, v108
	v_mul_f32_e32 v36, v36, v89
	v_mul_f32_e32 v108, v36, v108
	global_store_dword v134, v108, s[24:25]
	s_waitcnt vmcnt(31)
	v_lshlrev_b32_e32 v109, 16, v109
	v_mul_f32_e32 v4, v4, v89
	v_mul_f32_e32 v109, v4, v109
	global_store_dword v134, v109, s[26:27]
	s_waitcnt vmcnt(31)
	v_lshlrev_b32_e32 v110, 16, v110
	v_mul_f32_e32 v21, v21, v80
	v_mul_f32_e32 v110, v21, v110
	global_store_dword v134, v110, s[20:21] offset:2048
	s_waitcnt vmcnt(31)
	v_lshlrev_b32_e32 v111, 16, v111
	v_mul_f32_e32 v53, v53, v80
	v_mul_f32_e32 v111, v53, v111
	global_store_dword v134, v111, s[22:23] offset:2048
	s_waitcnt vmcnt(31)
	v_lshlrev_b32_e32 v112, 16, v112
	v_mul_f32_e32 v37, v37, v80
	v_mul_f32_e32 v112, v37, v112
	global_store_dword v134, v112, s[24:25] offset:2048
	s_waitcnt vmcnt(31)
	v_lshlrev_b32_e32 v113, 16, v113
	v_mul_f32_e32 v5, v5, v80
	v_mul_f32_e32 v113, v5, v113
	global_store_dword v134, v113, s[26:27] offset:2048
	s_add_u32 s20, s34, 0x2000
	s_addc_u32 s21, s35, 0
	s_add_u32 s22, s34, 0xa000
	s_addc_u32 s23, s35, 0
	s_add_u32 s24, s34, 0x12000
	s_addc_u32 s25, s35, 0
	s_add_u32 s26, s34, 0x1a000
	s_addc_u32 s27, s35, 0
	s_waitcnt vmcnt(31)
	v_lshlrev_b32_e32 v114, 16, v114
	v_mul_f32_e32 v22, v22, v79
	v_mul_f32_e32 v114, v22, v114
	global_store_dword v134, v114, s[20:21]
	s_waitcnt vmcnt(31)
	v_lshlrev_b32_e32 v115, 16, v115
	v_mul_f32_e32 v54, v54, v79
	v_mul_f32_e32 v115, v54, v115
	global_store_dword v134, v115, s[22:23]
	s_waitcnt vmcnt(31)
	v_lshlrev_b32_e32 v116, 16, v116
	v_mul_f32_e32 v38, v38, v79
	v_mul_f32_e32 v116, v38, v116
	global_store_dword v134, v116, s[24:25]
	s_waitcnt vmcnt(31)
	v_lshlrev_b32_e32 v117, 16, v117
	v_mul_f32_e32 v6, v6, v79
	v_mul_f32_e32 v117, v6, v117
	global_store_dword v134, v117, s[26:27]
	s_waitcnt vmcnt(31)
	v_lshlrev_b32_e32 v118, 16, v118
	v_mul_f32_e32 v23, v23, v78
	v_mul_f32_e32 v118, v23, v118
	global_store_dword v134, v118, s[20:21] offset:2048
	s_waitcnt vmcnt(31)
	v_lshlrev_b32_e32 v119, 16, v119
	v_mul_f32_e32 v55, v55, v78
	v_mul_f32_e32 v119, v55, v119
	global_store_dword v134, v119, s[22:23] offset:2048
	s_waitcnt vmcnt(31)
	v_lshlrev_b32_e32 v120, 16, v120
	v_mul_f32_e32 v39, v39, v78
	v_mul_f32_e32 v120, v39, v120
	global_store_dword v134, v120, s[24:25] offset:2048
	s_waitcnt vmcnt(31)
	v_lshlrev_b32_e32 v121, 16, v121
	v_mul_f32_e32 v7, v7, v78
	v_mul_f32_e32 v121, v7, v121
	global_store_dword v134, v121, s[26:27] offset:2048
	s_add_u32 s20, s34, 0x3000
	s_addc_u32 s21, s35, 0
	s_add_u32 s22, s34, 0xb000
	s_addc_u32 s23, s35, 0
	s_add_u32 s24, s34, 0x13000
	s_addc_u32 s25, s35, 0
	s_add_u32 s26, s34, 0x1b000
	s_addc_u32 s27, s35, 0
	s_waitcnt vmcnt(31)
	v_lshlrev_b32_e32 v122, 16, v122
	v_mul_f32_e32 v24, v24, v77
	v_mul_f32_e32 v122, v24, v122
	global_store_dword v134, v122, s[20:21]
	s_waitcnt vmcnt(31)
	v_lshlrev_b32_e32 v123, 16, v123
	v_mul_f32_e32 v56, v56, v77
	v_mul_f32_e32 v123, v56, v123
	global_store_dword v134, v123, s[22:23]
	s_waitcnt vmcnt(31)
	v_lshlrev_b32_e32 v124, 16, v124
	v_mul_f32_e32 v40, v40, v77
	v_mul_f32_e32 v124, v40, v124
	global_store_dword v134, v124, s[24:25]
	s_waitcnt vmcnt(31)
	v_lshlrev_b32_e32 v125, 16, v125
	v_mul_f32_e32 v8, v8, v77
	v_mul_f32_e32 v125, v8, v125
	global_store_dword v134, v125, s[26:27]
	s_waitcnt vmcnt(31)
	v_lshlrev_b32_e32 v126, 16, v126
	v_mul_f32_e32 v25, v25, v76
	v_mul_f32_e32 v126, v25, v126
	global_store_dword v134, v126, s[20:21] offset:2048
	s_waitcnt vmcnt(31)
	v_lshlrev_b32_e32 v127, 16, v127
	v_mul_f32_e32 v57, v57, v76
	v_mul_f32_e32 v127, v57, v127
	global_store_dword v134, v127, s[22:23] offset:2048
	s_waitcnt vmcnt(31)
	v_lshlrev_b32_e32 v128, 16, v128
	v_mul_f32_e32 v41, v41, v76
	v_mul_f32_e32 v128, v41, v128
	global_store_dword v134, v128, s[24:25] offset:2048
	s_waitcnt vmcnt(31)
; __device__ __forceinline__ float bf2f(bf16_t v) { return __uint_as_float(((unsigned)v) << 16); }
; __device__ __forceinline__ int crow(int r, int hi) { return (r & 3) + 8 * (r >> 2) + 4 * hi; }
; template <int MODE>
; __device__ __forceinline__ void attn_body(const bf16_t* __restrict__ Qb, const bf16_t* __restrict__ Kh, const bf16_t* __restrict__ Vh, int NT, int krel0,
;                                           char* lds, const float* __restrict__ lutg, const AttnEpi& E) {
;     ...
;     for (int r = 0; r < 16; ++r) { const int row = rowb + crow(r, hi);
; #pragma unroll
;       for (int d0 = 0; d0 < 4; ++d0) { const int idx = (d0 * 16 + r) * 512 + tid;
;         const float g = bf2f(E.gate[(size_t)row * GW + d0 * 32 + r32]);
;         const float v = o[d0][r] * rli[r] * g;
;         if constexpr (MODE == 0) pk0[idx] = v; else pk0[idx] += v; } }
	v_lshlrev_b32_e32 v129, 16, v129
	v_mul_f32_e32 v9, v9, v76
	v_mul_f32_e32 v129, v9, v129
	global_store_dword v134, v129, s[26:27] offset:2048
	v_or_b32_e32 v132, 16, v0
	v_mad_i64_i32 v[130:131], s[28:29], v132, s88, v[66:67]
	global_load_ushort v136, v[130:131], off
	global_load_ushort v137, v[130:131], off offset:64
	global_load_ushort v138, v[130:131], off offset:128
	global_load_ushort v139, v[130:131], off offset:192
	v_or_b32_e32 v132, 17, v0
	v_mad_i64_i32 v[130:131], s[28:29], v132, s88, v[66:67]
	global_load_ushort v140, v[130:131], off
	global_load_ushort v141, v[130:131], off offset:64
	global_load_ushort v142, v[130:131], off offset:128
	global_load_ushort v143, v[130:131], off offset:192
	v_or_b32_e32 v132, 18, v0
	v_mad_i64_i32 v[130:131], s[28:29], v132, s88, v[66:67]
	global_load_ushort v144, v[130:131], off
	global_load_ushort v145, v[130:131], off offset:64
	global_load_ushort v146, v[130:131], off offset:128
	global_load_ushort v147, v[130:131], off offset:192
	v_or_b32_e32 v132, 19, v0
	v_mad_i64_i32 v[130:131], s[28:29], v132, s88, v[66:67]
	global_load_ushort v148, v[130:131], off
	global_load_ushort v149, v[130:131], off offset:64
	global_load_ushort v150, v[130:131], off offset:128
	global_load_ushort v151, v[130:131], off offset:192
	v_or_b32_e32 v132, 24, v0
	v_mad_i64_i32 v[130:131], s[28:29], v132, s88, v[66:67]
	global_load_ushort v152, v[130:131], off
	global_load_ushort v153, v[130:131], off offset:64
	global_load_ushort v154, v[130:131], off offset:128
	global_load_ushort v155, v[130:131], off offset:192
	v_or_b32_e32 v132, 25, v0
	v_mad_i64_i32 v[130:131], s[28:29], v132, s88, v[66:67]
	global_load_ushort v156, v[130:131], off
	global_load_ushort v157, v[130:131], off offset:64
	global_load_ushort v158, v[130:131], off offset:128
	global_load_ushort v159, v[130:131], off offset:192
	v_or_b32_e32 v132, 26, v0
	v_mad_i64_i32 v[130:131], s[28:29], v132, s88, v[66:67]
	global_load_ushort v160, v[130:131], off
	global_load_ushort v161, v[130:131], off offset:64
	global_load_ushort v162, v[130:131], off offset:128
	global_load_ushort v163, v[130:131], off offset:192
	v_or_b32_e32 v132, 27, v0
	v_mad_i64_i32 v[130:131], s[28:29], v132, s88, v[66:67]
	global_load_ushort v164, v[130:131], off
	global_load_ushort v165, v[130:131], off offset:64
	global_load_ushort v166, v[130:131], off offset:128
	global_load_ushort v167, v[130:131], off offset:192
	s_add_u32 s20, s34, 0x4000
	s_addc_u32 s21, s35, 0
	s_add_u32 s22, s34, 0xc000
	s_addc_u32 s23, s35, 0
	s_add_u32 s24, s34, 0x14000
	s_addc_u32 s25, s35, 0
	s_add_u32 s26, s34, 0x1c000
	s_addc_u32 s27, s35, 0
	s_waitcnt vmcnt(31)
	v_lshlrev_b32_e32 v136, 16, v136
	v_mul_f32_e32 v26, v26, v75
	v_mul_f32_e32 v136, v26, v136
	global_store_dword v134, v136, s[20:21]
	s_waitcnt vmcnt(31)
	v_lshlrev_b32_e32 v137, 16, v137
	v_mul_f32_e32 v58, v58, v75
	v_mul_f32_e32 v137, v58, v137
	global_store_dword v134, v137, s[22:23]
	s_waitcnt vmcnt(31)
	v_lshlrev_b32_e32 v138, 16, v138
	v_mul_f32_e32 v42, v42, v75
	v_mul_f32_e32 v138, v42, v138
	global_store_dword v134, v138, s[24:25]
	s_waitcnt vmcnt(31)
	v_lshlrev_b32_e32 v139, 16, v139
	v_mul_f32_e32 v10, v10, v75
	v_mul_f32_e32 v139, v10, v139
	global_store_dword v134, v139, s[26:27]
	s_waitcnt vmcnt(31)
	v_lshlrev_b32_e32 v140, 16, v140
	v_mul_f32_e32 v27, v27, v74
	v_mul_f32_e32 v140, v27, v140
	global_store_dword v134, v140, s[20:21] offset:2048
	s_waitcnt vmcnt(31)
	v_lshlrev_b32_e32 v141, 16, v141
	v_mul_f32_e32 v59, v59, v74
	v_mul_f32_e32 v141, v59, v141
	global_store_dword v134, v141, s[22:23] offset:2048
	s_waitcnt vmcnt(31)
	v_lshlrev_b32_e32 v142, 16, v142
	v_mul_f32_e32 v43, v43, v74
	v_mul_f32_e32 v142, v43, v142
	global_store_dword v134, v142, s[24:25] offset:2048
	s_waitcnt vmcnt(31)
	v_lshlrev_b32_e32 v143, 16, v143
	v_mul_f32_e32 v11, v11, v74
	v_mul_f32_e32 v143, v11, v143
	global_store_dword v134, v143, s[26:27] offset:2048
	s_add_u32 s20, s34, 0x5000
	s_addc_u32 s21, s35, 0
	s_add_u32 s22, s34, 0xd000
	s_addc_u32 s23, s35, 0
	s_add_u32 s24, s34, 0x15000
	s_addc_u32 s25, s35, 0
	s_add_u32 s26, s34, 0x1d000
	s_addc_u32 s27, s35, 0
	s_waitcnt vmcnt(31)
	v_lshlrev_b32_e32 v144, 16, v144
	v_mul_f32_e32 v28, v28, v73
	v_mul_f32_e32 v144, v28, v144
	global_store_dword v134, v144, s[20:21]
	s_waitcnt vmcnt(31)
	v_lshlrev_b32_e32 v145, 16, v145
	v_mul_f32_e32 v60, v60, v73
	v_mul_f32_e32 v145, v60, v145
	global_store_dword v134, v145, s[22:23]
	s_waitcnt vmcnt(31)
; __device__ __forceinline__ float bf2f(bf16_t v) { return __uint_as_float(((unsigned)v) << 16); }
; __device__ __forceinline__ int crow(int r, int hi) { return (r & 3) + 8 * (r >> 2) + 4 * hi; }
; template <int MODE>
; __device__ __forceinline__ void attn_body(const bf16_t* __restrict__ Qb, const bf16_t* __restrict__ Kh, const bf16_t* __restrict__ Vh, int NT, int krel0,
;                                           char* lds, const float* __restrict__ lutg, const AttnEpi& E) {
;     ...
;     for (int r = 0; r < 16; ++r) { const int row = rowb + crow(r, hi);
; #pragma unroll
;       for (int d0 = 0; d0 < 4; ++d0) { const int idx = (d0 * 16 + r) * 512 + tid;
;         const float g = bf2f(E.gate[(size_t)row * GW + d0 * 32 + r32]);
;         const float v = o[d0][r] * rli[r] * g;
;         if constexpr (MODE == 0) pk0[idx] = v; else pk0[idx] += v; } }
; __device__ __forceinline__ void phase_attn(const Params& p, int l, unsigned char* shm) {
;     ...
;     { const int t_lo = max(0, 4 * qb - 2), t_hi = min(S / 64, 4 * qb + 6);
;       const bf16_t* kb = seqK + (size_t)t_lo * 64 * QKVW;
;       E.gate = grow + 1024; E.gq = p.in[13] + l * 128;
;       attn_body<1>(rowQ + 1536 + h * 128, kb + 2560 + g * 128, kb + 2816 + g * 128, t_hi - t_lo, t_lo * 64 - q0, (char*)shm, lutall + h * 259, E); }
	v_lshlrev_b32_e32 v146, 16, v146
	v_mul_f32_e32 v44, v44, v73
	v_mul_f32_e32 v146, v44, v146
	global_store_dword v134, v146, s[24:25]
	s_waitcnt vmcnt(31)
	v_lshlrev_b32_e32 v147, 16, v147
	v_mul_f32_e32 v12, v12, v73
	v_mul_f32_e32 v147, v12, v147
	global_store_dword v134, v147, s[26:27]
	s_waitcnt vmcnt(31)
	v_lshlrev_b32_e32 v148, 16, v148
	v_mul_f32_e32 v29, v29, v72
	v_mul_f32_e32 v148, v29, v148
	global_store_dword v134, v148, s[20:21] offset:2048
	s_waitcnt vmcnt(31)
	v_lshlrev_b32_e32 v149, 16, v149
	v_mul_f32_e32 v61, v61, v72
	v_mul_f32_e32 v149, v61, v149
	global_store_dword v134, v149, s[22:23] offset:2048
	s_waitcnt vmcnt(31)
	v_lshlrev_b32_e32 v150, 16, v150
	v_mul_f32_e32 v45, v45, v72
	v_mul_f32_e32 v150, v45, v150
	global_store_dword v134, v150, s[24:25] offset:2048
	s_waitcnt vmcnt(31)
	v_lshlrev_b32_e32 v151, 16, v151
	v_mul_f32_e32 v13, v13, v72
	v_mul_f32_e32 v151, v13, v151
	global_store_dword v134, v151, s[26:27] offset:2048
	s_add_u32 s20, s34, 0x6000
	s_addc_u32 s21, s35, 0
	s_add_u32 s22, s34, 0xe000
	s_addc_u32 s23, s35, 0
	s_add_u32 s24, s34, 0x16000
	s_addc_u32 s25, s35, 0
	s_add_u32 s26, s34, 0x1e000
	s_addc_u32 s27, s35, 0
	s_waitcnt vmcnt(31)
	v_lshlrev_b32_e32 v152, 16, v152
	v_mul_f32_e32 v30, v30, v71
	v_mul_f32_e32 v152, v30, v152
	global_store_dword v134, v152, s[20:21]
	s_waitcnt vmcnt(31)
	v_lshlrev_b32_e32 v153, 16, v153
	v_mul_f32_e32 v62, v62, v71
	v_mul_f32_e32 v153, v62, v153
	global_store_dword v134, v153, s[22:23]
	s_waitcnt vmcnt(31)
	v_lshlrev_b32_e32 v154, 16, v154
	v_mul_f32_e32 v46, v46, v71
	v_mul_f32_e32 v154, v46, v154
	global_store_dword v134, v154, s[24:25]
	s_waitcnt vmcnt(31)
	v_lshlrev_b32_e32 v155, 16, v155
	v_mul_f32_e32 v14, v14, v71
	v_mul_f32_e32 v155, v14, v155
	global_store_dword v134, v155, s[26:27]
	s_waitcnt vmcnt(31)
	v_lshlrev_b32_e32 v156, 16, v156
	v_mul_f32_e32 v31, v31, v70
	v_mul_f32_e32 v156, v31, v156
	global_store_dword v134, v156, s[20:21] offset:2048
	s_waitcnt vmcnt(31)
	v_lshlrev_b32_e32 v157, 16, v157
	v_mul_f32_e32 v63, v63, v70
	v_mul_f32_e32 v157, v63, v157
	global_store_dword v134, v157, s[22:23] offset:2048
	s_waitcnt vmcnt(31)
	v_lshlrev_b32_e32 v158, 16, v158
	v_mul_f32_e32 v47, v47, v70
	v_mul_f32_e32 v158, v47, v158
	global_store_dword v134, v158, s[24:25] offset:2048
	s_waitcnt vmcnt(31)
	v_lshlrev_b32_e32 v159, 16, v159
	v_mul_f32_e32 v15, v15, v70
	v_mul_f32_e32 v159, v15, v159
	global_store_dword v134, v159, s[26:27] offset:2048
	s_add_u32 s20, s34, 0x7000
	s_addc_u32 s21, s35, 0
	s_add_u32 s22, s34, 0xf000
	s_addc_u32 s23, s35, 0
	s_add_u32 s24, s34, 0x17000
	s_addc_u32 s25, s35, 0
	s_add_u32 s26, s34, 0x1f000
	s_addc_u32 s27, s35, 0
	s_waitcnt vmcnt(31)
	v_lshlrev_b32_e32 v160, 16, v160
	v_mul_f32_e32 v32, v32, v69
	v_mul_f32_e32 v160, v32, v160
	global_store_dword v134, v160, s[20:21]
	s_waitcnt vmcnt(31)
	v_lshlrev_b32_e32 v161, 16, v161
	v_mul_f32_e32 v64, v64, v69
	v_mul_f32_e32 v161, v64, v161
	global_store_dword v134, v161, s[22:23]
	s_waitcnt vmcnt(31)
	v_lshlrev_b32_e32 v162, 16, v162
	v_mul_f32_e32 v48, v48, v69
	v_mul_f32_e32 v162, v48, v162
	global_store_dword v134, v162, s[24:25]
	s_waitcnt vmcnt(31)
	v_lshlrev_b32_e32 v163, 16, v163
	v_mul_f32_e32 v16, v16, v69
	v_mul_f32_e32 v163, v16, v163
	global_store_dword v134, v163, s[26:27]
	s_waitcnt vmcnt(31)
	v_lshlrev_b32_e32 v164, 16, v164
	v_mul_f32_e32 v33, v33, v68
	v_mul_f32_e32 v164, v33, v164
	global_store_dword v134, v164, s[20:21] offset:2048
	s_waitcnt vmcnt(31)
	v_lshlrev_b32_e32 v165, 16, v165
	v_mul_f32_e32 v65, v65, v68
	v_mul_f32_e32 v165, v65, v165
	global_store_dword v134, v165, s[22:23] offset:2048
	s_waitcnt vmcnt(31)
	v_lshlrev_b32_e32 v166, 16, v166
	v_mul_f32_e32 v49, v49, v68
	v_mul_f32_e32 v166, v49, v166
	global_store_dword v134, v166, s[24:25] offset:2048
	s_waitcnt vmcnt(31)
	v_lshlrev_b32_e32 v167, 16, v167
	v_mul_f32_e32 v17, v17, v68
	v_mul_f32_e32 v167, v17, v167
	global_store_dword v134, v167, s[26:27] offset:2048
	s_mulk_i32 s59, 0x40c
	s_lshl_b32 s0, s58, 2
	s_max_i32 s63, s0, 2
	s_add_i32 s0, s0, 6
	s_min_i32 s66, s11, s0
	v_readlane_b32 s0, v252, 45
	v_readlane_b32 s1, v252, 46
	s_add_u32 s58, s0, s59
	s_movk_i32 s0, 0x103
	s_addc_u32 s59, s1, 0
	v_mov_b32_e32 v188, v179
	s_nop 0
	v_cmp_gt_i32_e32 vcc, s0, v188
	v_ashrrev_i32_e32 v189, 31, v188
	s_barrier
	s_and_saveexec_b64 s[0:1], vcc
	s_cbranch_execz .LBB0_99
	v_lshl_add_u64 v[2:3], v[188:189], 2, s[58:59]
	global_load_dword v2, v[2:3], off
	v_lshl_add_u32 v0, v188, 2, 0
	v_add_u32_e32 v0, 0x18800, v0
	s_waitcnt vmcnt(0)
	ds_write_b32 v0, v2
